# plus: K-nope GEMM epilogue row-scale loads prefetched together
# speedup vs baseline: 1.0289x; 1.0050x over previous
.LBB0_482:
	s_add_u32 s10, s80, 0x100
	s_addc_u32 s11, s81, 0
	s_add_i32 s2, 0, 0x10000
	v_add_u32_e32 v156, s2, v145
	ds_read_b128 v[140:143], v156
	ds_read_b128 v[148:151], v156 offset:1024
	ds_read_b128 v[152:155], v156 offset:2048
	ds_read_b128 v[156:159], v156 offset:3072
	s_cmp_eq_u32 s44, 4
	s_cselect_b32 s93, s77, s11
	s_cselect_b32 s92, s76, s10
	s_cselect_b32 s83, s24, s47
	s_cselect_b32 s82, s25, s46
	v_lshl_add_u64 v[164:165], s[80:81], 0, v[136:137]
	s_add_i32 m0, s58, 0xc000
	ds_read_b128 v[160:163], v147
	ds_read_b128 v[188:191], v147 offset:1024
	ds_read_b128 v[192:195], v147 offset:2048
	ds_read_b128 v[196:199], v147 offset:3072
	ds_read_b128 v[200:203], v147 offset:4096
	ds_read_b128 v[216:219], v147 offset:5120
	ds_read_b128 v[220:223], v147 offset:6144
	ds_read_b128 v[224:227], v147 offset:7168
	global_load_lds_dwordx4 v[164:165], off
	v_lshl_add_u64 v[164:165], s[80:81], 0, v[138:139]
	s_add_i32 m0, s58, 0xe000
	s_nop 0
	global_load_lds_dwordx4 v[164:165], off
	s_waitcnt lgkmcnt(8)
	s_barrier
	s_waitcnt lgkmcnt(0)
	s_setprio 1
	s_waitcnt lgkmcnt(0)
	v_mfma_f32_16x16x32_bf16 v[126:129], v[140:143], v[160:163], v[126:129]
	v_mfma_f32_16x16x32_bf16 v[122:125], v[152:155], v[160:163], v[122:125]
	v_mfma_f32_16x16x32_bf16 v[110:113], v[140:143], v[192:195], v[110:113]
	v_mfma_f32_16x16x32_bf16 v[106:109], v[152:155], v[192:195], v[106:109]
	v_mfma_f32_16x16x32_bf16 v[94:97], v[140:143], v[200:203], v[94:97]
	v_mfma_f32_16x16x32_bf16 v[90:93], v[152:155], v[200:203], v[90:93]
	v_mfma_f32_16x16x32_bf16 v[78:81], v[140:143], v[220:223], v[78:81]
	v_mfma_f32_16x16x32_bf16 v[74:77], v[152:155], v[220:223], v[74:77]
	v_mfma_f32_16x16x32_bf16 v[126:129], v[148:151], v[188:191], v[126:129]
	v_mfma_f32_16x16x32_bf16 v[122:125], v[156:159], v[188:191], v[122:125]
	v_mfma_f32_16x16x32_bf16 v[110:113], v[148:151], v[196:199], v[110:113]
	v_mfma_f32_16x16x32_bf16 v[106:109], v[156:159], v[196:199], v[106:109]
	v_mfma_f32_16x16x32_bf16 v[94:97], v[148:151], v[216:219], v[94:97]
	v_mfma_f32_16x16x32_bf16 v[90:93], v[156:159], v[216:219], v[90:93]
	v_mfma_f32_16x16x32_bf16 v[78:81], v[148:151], v[224:227], v[78:81]
	v_mfma_f32_16x16x32_bf16 v[74:77], v[156:159], v[224:227], v[74:77]
	s_setprio 0
	s_barrier
	s_add_i32 s17, 0, 0x14000
	v_add_u32_e32 v164, s17, v145
	s_add_i32 s2, s2, s3
	ds_read_b128 v[228:231], v164
	ds_read_b128 v[232:235], v164 offset:1024
	ds_read_b128 v[236:239], v164 offset:2048
	ds_read_b128 v[240:243], v164 offset:3072
	v_lshl_add_u64 v[164:165], s[82:83], 0, v[0:1]
	s_mov_b32 m0, s2
	v_lshl_add_u64 v[204:205], s[82:83], 0, v[130:131]
	global_load_lds_dwordx4 v[164:165], off
	s_add_i32 m0, s2, 0x2000
	s_nop 0
	global_load_lds_dwordx4 v[204:205], off
	s_barrier
	s_waitcnt lgkmcnt(0)
	s_setprio 1
	s_waitcnt lgkmcnt(0)
	v_mfma_f32_16x16x32_bf16 v[118:121], v[228:231], v[160:163], v[118:121]
	v_mfma_f32_16x16x32_bf16 v[114:117], v[236:239], v[160:163], v[114:117]
	v_mfma_f32_16x16x32_bf16 v[102:105], v[228:231], v[192:195], v[102:105]
	v_mfma_f32_16x16x32_bf16 v[98:101], v[236:239], v[192:195], v[98:101]
	v_mfma_f32_16x16x32_bf16 v[86:89], v[228:231], v[200:203], v[86:89]
	v_mfma_f32_16x16x32_bf16 v[82:85], v[236:239], v[200:203], v[82:85]
	v_mfma_f32_16x16x32_bf16 v[70:73], v[228:231], v[220:223], v[70:73]
	v_mfma_f32_16x16x32_bf16 v[66:69], v[236:239], v[220:223], v[66:69]
	v_mfma_f32_16x16x32_bf16 v[118:121], v[232:235], v[188:191], v[118:121]
	v_mfma_f32_16x16x32_bf16 v[114:117], v[240:243], v[188:191], v[114:117]
	v_mfma_f32_16x16x32_bf16 v[102:105], v[232:235], v[196:199], v[102:105]
	v_mfma_f32_16x16x32_bf16 v[98:101], v[240:243], v[196:199], v[98:101]
	v_mfma_f32_16x16x32_bf16 v[86:89], v[232:235], v[216:219], v[86:89]
	v_mfma_f32_16x16x32_bf16 v[82:85], v[240:243], v[216:219], v[82:85]
	v_mfma_f32_16x16x32_bf16 v[70:73], v[232:235], v[224:227], v[70:73]
	v_mfma_f32_16x16x32_bf16 v[66:69], v[240:243], v[224:227], v[66:69]
	s_setprio 0
	s_mov_b32 m0, s58
	v_lshl_add_u64 v[244:245], s[92:93], 0, v[134:135]
	s_barrier
	ds_read_b128 v[160:163], v147 offset:16384
	ds_read_b128 v[188:191], v147 offset:17408
	ds_read_b128 v[192:195], v147 offset:18432
	ds_read_b128 v[196:199], v147 offset:19456
	ds_read_b128 v[200:203], v147 offset:20480
	ds_read_b128 v[216:219], v147 offset:21504
	ds_read_b128 v[220:223], v147 offset:22528
	ds_read_b128 v[224:227], v147 offset:23552
	global_load_lds_dwordx4 v[244:245], off
	v_lshl_add_u64 v[246:247], s[92:93], 0, v[132:133]
	s_mov_b32 m0, s69
	s_nop 0
	global_load_lds_dwordx4 v[246:247], off
	s_barrier
	s_waitcnt lgkmcnt(0)
	s_setprio 1
	s_waitcnt lgkmcnt(0)
	v_mfma_f32_16x16x32_bf16 v[62:65], v[140:143], v[160:163], v[62:65]
	v_mfma_f32_16x16x32_bf16 v[58:61], v[152:155], v[160:163], v[58:61]
	v_mfma_f32_16x16x32_bf16 v[46:49], v[140:143], v[192:195], v[46:49]
	v_mfma_f32_16x16x32_bf16 v[42:45], v[152:155], v[192:195], v[42:45]
	v_mfma_f32_16x16x32_bf16 v[30:33], v[140:143], v[200:203], v[30:33]
	v_mfma_f32_16x16x32_bf16 v[26:29], v[152:155], v[200:203], v[26:29]
	v_mfma_f32_16x16x32_bf16 v[14:17], v[140:143], v[220:223], v[14:17]
	v_mfma_f32_16x16x32_bf16 v[10:13], v[152:155], v[220:223], v[10:13]
	v_mfma_f32_16x16x32_bf16 v[62:65], v[148:151], v[188:191], v[62:65]
	v_mfma_f32_16x16x32_bf16 v[58:61], v[156:159], v[188:191], v[58:61]
	v_mfma_f32_16x16x32_bf16 v[46:49], v[148:151], v[196:199], v[46:49]
	v_mfma_f32_16x16x32_bf16 v[42:45], v[156:159], v[196:199], v[42:45]
	v_mfma_f32_16x16x32_bf16 v[30:33], v[148:151], v[216:219], v[30:33]
	v_mfma_f32_16x16x32_bf16 v[26:29], v[156:159], v[216:219], v[26:29]
	v_mfma_f32_16x16x32_bf16 v[14:17], v[148:151], v[224:227], v[14:17]
	v_mfma_f32_16x16x32_bf16 v[10:13], v[156:159], v[224:227], v[10:13]
	s_setprio 0
	s_barrier
	s_add_u32 s26, s82, 0x20000
	s_addc_u32 s27, s83, 0
	s_add_i32 s2, s17, s3
	v_lshl_add_u64 v[140:141], s[26:27], 0, v[0:1]
	s_mov_b32 m0, s2
	s_nop 0
	global_load_lds_dwordx4 v[140:141], off
	v_lshl_add_u64 v[140:141], s[26:27], 0, v[130:131]
	s_add_i32 m0, s2, 0x2000
	s_nop 0
	global_load_lds_dwordx4 v[140:141], off
	s_waitcnt vmcnt(6)
	s_barrier
	s_setprio 1
	v_mfma_f32_16x16x32_bf16 v[54:57], v[228:231], v[160:163], v[54:57]
	v_mfma_f32_16x16x32_bf16 v[50:53], v[236:239], v[160:163], v[50:53]
	v_mfma_f32_16x16x32_bf16 v[38:41], v[228:231], v[192:195], v[38:41]
	v_mfma_f32_16x16x32_bf16 v[34:37], v[236:239], v[192:195], v[34:37]
	v_mfma_f32_16x16x32_bf16 v[22:25], v[228:231], v[200:203], v[22:25]
	v_mfma_f32_16x16x32_bf16 v[18:21], v[236:239], v[200:203], v[18:21]
	v_mfma_f32_16x16x32_bf16 v[6:9], v[228:231], v[220:223], v[6:9]
	v_mfma_f32_16x16x32_bf16 v[2:5], v[236:239], v[220:223], v[2:5]
	v_mfma_f32_16x16x32_bf16 v[54:57], v[232:235], v[188:191], v[54:57]
	v_mfma_f32_16x16x32_bf16 v[50:53], v[240:243], v[188:191], v[50:53]
	v_mfma_f32_16x16x32_bf16 v[38:41], v[232:235], v[196:199], v[38:41]
	v_mfma_f32_16x16x32_bf16 v[34:37], v[240:243], v[196:199], v[34:37]
	v_mfma_f32_16x16x32_bf16 v[22:25], v[232:235], v[216:219], v[22:25]
	v_mfma_f32_16x16x32_bf16 v[18:21], v[240:243], v[216:219], v[18:21]
	v_mfma_f32_16x16x32_bf16 v[6:9], v[232:235], v[224:227], v[6:9]
	v_mfma_f32_16x16x32_bf16 v[2:5], v[240:243], v[224:227], v[2:5]
	s_setprio 0
	s_add_i32 s2, 0, 0x18000
	v_add_u32_e32 v156, s2, v145
	s_barrier
	ds_read_b128 v[140:143], v156
	ds_read_b128 v[148:151], v156 offset:1024
	ds_read_b128 v[152:155], v156 offset:2048
	ds_read_b128 v[156:159], v156 offset:3072
	s_add_u32 s26, s92, 0xd0000
	s_addc_u32 s27, s93, 0
	s_mov_b32 m0, s70
	v_lshl_add_u64 v[228:229], s[26:27], 0, v[134:135]
	ds_read_b128 v[160:163], v147 offset:32768
	ds_read_b128 v[188:191], v147 offset:33792
	ds_read_b128 v[192:195], v147 offset:34816
	ds_read_b128 v[196:199], v147 offset:35840
	ds_read_b128 v[200:203], v147 offset:36864
	ds_read_b128 v[216:219], v147 offset:37888
	ds_read_b128 v[220:223], v147 offset:38912
	ds_read_b128 v[224:227], v147 offset:39936
	global_load_lds_dwordx4 v[228:229], off
	v_lshl_add_u64 v[228:229], s[26:27], 0, v[132:133]
	s_mov_b32 m0, s71
	s_nop 0
	global_load_lds_dwordx4 v[228:229], off
	s_waitcnt lgkmcnt(8)
	s_barrier
	s_waitcnt lgkmcnt(0)
	s_setprio 1
	s_waitcnt lgkmcnt(0)
	v_mfma_f32_16x16x32_bf16 v[126:129], v[140:143], v[160:163], v[126:129]
	v_mfma_f32_16x16x32_bf16 v[122:125], v[152:155], v[160:163], v[122:125]
	v_mfma_f32_16x16x32_bf16 v[110:113], v[140:143], v[192:195], v[110:113]
	v_mfma_f32_16x16x32_bf16 v[106:109], v[152:155], v[192:195], v[106:109]
	v_mfma_f32_16x16x32_bf16 v[94:97], v[140:143], v[200:203], v[94:97]
	v_mfma_f32_16x16x32_bf16 v[90:93], v[152:155], v[200:203], v[90:93]
	v_mfma_f32_16x16x32_bf16 v[78:81], v[140:143], v[220:223], v[78:81]
	v_mfma_f32_16x16x32_bf16 v[74:77], v[152:155], v[220:223], v[74:77]
	v_mfma_f32_16x16x32_bf16 v[126:129], v[148:151], v[188:191], v[126:129]
	v_mfma_f32_16x16x32_bf16 v[122:125], v[156:159], v[188:191], v[122:125]
	v_mfma_f32_16x16x32_bf16 v[110:113], v[148:151], v[196:199], v[110:113]
	v_mfma_f32_16x16x32_bf16 v[106:109], v[156:159], v[196:199], v[106:109]
	v_mfma_f32_16x16x32_bf16 v[94:97], v[148:151], v[216:219], v[94:97]
	v_mfma_f32_16x16x32_bf16 v[90:93], v[156:159], v[216:219], v[90:93]
	v_mfma_f32_16x16x32_bf16 v[78:81], v[148:151], v[224:227], v[78:81]
	v_mfma_f32_16x16x32_bf16 v[74:77], v[156:159], v[224:227], v[74:77]
	s_setprio 0
	s_barrier
	s_add_i32 s17, 0, 0x1c000
	s_add_i32 s2, s2, s3
	v_add_u32_e32 v206, s17, v145
	v_lshl_add_u64 v[164:165], v[164:165], 0, s[28:29]
	s_mov_b32 m0, s2
	ds_read_b128 v[228:231], v206
	ds_read_b128 v[232:235], v206 offset:1024
	ds_read_b128 v[236:239], v206 offset:2048
	ds_read_b128 v[240:243], v206 offset:3072
	global_load_lds_dwordx4 v[164:165], off
	v_lshl_add_u64 v[164:165], v[204:205], 0, s[28:29]
	s_add_i32 m0, s2, 0x2000
	s_nop 0
	global_load_lds_dwordx4 v[164:165], off
	s_barrier
	s_waitcnt lgkmcnt(0)
	s_setprio 1
	s_waitcnt lgkmcnt(0)
	v_mfma_f32_16x16x32_bf16 v[118:121], v[228:231], v[160:163], v[118:121]
	v_mfma_f32_16x16x32_bf16 v[114:117], v[236:239], v[160:163], v[114:117]
	v_mfma_f32_16x16x32_bf16 v[102:105], v[228:231], v[192:195], v[102:105]
	v_mfma_f32_16x16x32_bf16 v[98:101], v[236:239], v[192:195], v[98:101]
	v_mfma_f32_16x16x32_bf16 v[86:89], v[228:231], v[200:203], v[86:89]
	v_mfma_f32_16x16x32_bf16 v[82:85], v[236:239], v[200:203], v[82:85]
	v_mfma_f32_16x16x32_bf16 v[70:73], v[228:231], v[220:223], v[70:73]
	v_mfma_f32_16x16x32_bf16 v[66:69], v[236:239], v[220:223], v[66:69]
	v_mfma_f32_16x16x32_bf16 v[118:121], v[232:235], v[188:191], v[118:121]
	v_mfma_f32_16x16x32_bf16 v[114:117], v[240:243], v[188:191], v[114:117]
	v_mfma_f32_16x16x32_bf16 v[102:105], v[232:235], v[196:199], v[102:105]
	v_mfma_f32_16x16x32_bf16 v[98:101], v[240:243], v[196:199], v[98:101]
	v_mfma_f32_16x16x32_bf16 v[86:89], v[232:235], v[216:219], v[86:89]
	v_mfma_f32_16x16x32_bf16 v[82:85], v[240:243], v[216:219], v[82:85]
	v_mfma_f32_16x16x32_bf16 v[70:73], v[232:235], v[224:227], v[70:73]
	v_mfma_f32_16x16x32_bf16 v[66:69], v[240:243], v[224:227], v[66:69]
	s_setprio 0
	s_mov_b32 m0, s72
	v_lshl_add_u64 v[164:165], v[244:245], 0, s[28:29]
	s_barrier
	ds_read_b128 v[160:163], v147 offset:49152
	ds_read_b128 v[188:191], v147 offset:50176
	ds_read_b128 v[192:195], v147 offset:51200
	ds_read_b128 v[196:199], v147 offset:52224
	ds_read_b128 v[200:203], v147 offset:53248
	ds_read_b128 v[216:219], v147 offset:54272
	ds_read_b128 v[220:223], v147 offset:55296
	ds_read_b128 v[224:227], v147 offset:56320
	global_load_lds_dwordx4 v[164:165], off
	v_lshl_add_u64 v[164:165], v[246:247], 0, s[28:29]
	s_mov_b32 m0, s73
	s_nop 0
	global_load_lds_dwordx4 v[164:165], off
	s_barrier
	s_waitcnt lgkmcnt(0)
	s_setprio 1
	s_waitcnt lgkmcnt(0)
	v_mfma_f32_16x16x32_bf16 v[62:65], v[140:143], v[160:163], v[62:65]
	v_mfma_f32_16x16x32_bf16 v[58:61], v[152:155], v[160:163], v[58:61]
	v_mfma_f32_16x16x32_bf16 v[46:49], v[140:143], v[192:195], v[46:49]
	v_mfma_f32_16x16x32_bf16 v[42:45], v[152:155], v[192:195], v[42:45]
	v_mfma_f32_16x16x32_bf16 v[30:33], v[140:143], v[200:203], v[30:33]
	v_mfma_f32_16x16x32_bf16 v[26:29], v[152:155], v[200:203], v[26:29]
	v_mfma_f32_16x16x32_bf16 v[14:17], v[140:143], v[220:223], v[14:17]
	v_mfma_f32_16x16x32_bf16 v[10:13], v[152:155], v[220:223], v[10:13]
	v_mfma_f32_16x16x32_bf16 v[62:65], v[148:151], v[188:191], v[62:65]
	v_mfma_f32_16x16x32_bf16 v[58:61], v[156:159], v[188:191], v[58:61]
	v_mfma_f32_16x16x32_bf16 v[46:49], v[148:151], v[196:199], v[46:49]
	v_mfma_f32_16x16x32_bf16 v[42:45], v[156:159], v[196:199], v[42:45]
	v_mfma_f32_16x16x32_bf16 v[30:33], v[148:151], v[216:219], v[30:33]
	v_mfma_f32_16x16x32_bf16 v[26:29], v[156:159], v[216:219], v[26:29]
	v_mfma_f32_16x16x32_bf16 v[14:17], v[148:151], v[224:227], v[14:17]
	v_mfma_f32_16x16x32_bf16 v[10:13], v[156:159], v[224:227], v[10:13]
	s_setprio 0
	s_barrier
	s_add_u32 s26, s82, 0x20080
	s_addc_u32 s27, s83, 0
	s_add_i32 s2, s17, s3
	v_lshl_add_u64 v[140:141], s[26:27], 0, v[0:1]
	s_mov_b32 m0, s2
	s_nop 0
	global_load_lds_dwordx4 v[140:141], off
	v_lshl_add_u64 v[140:141], s[26:27], 0, v[130:131]
	s_add_i32 m0, s2, 0x2000
	s_nop 0
	global_load_lds_dwordx4 v[140:141], off
	s_waitcnt vmcnt(6)
	s_barrier
	s_setprio 1
	v_mfma_f32_16x16x32_bf16 v[54:57], v[228:231], v[160:163], v[54:57]
	v_mfma_f32_16x16x32_bf16 v[50:53], v[236:239], v[160:163], v[50:53]
	v_mfma_f32_16x16x32_bf16 v[38:41], v[228:231], v[192:195], v[38:41]
	v_mfma_f32_16x16x32_bf16 v[34:37], v[236:239], v[192:195], v[34:37]
	v_mfma_f32_16x16x32_bf16 v[22:25], v[228:231], v[200:203], v[22:25]
	v_mfma_f32_16x16x32_bf16 v[18:21], v[236:239], v[200:203], v[18:21]
	v_mfma_f32_16x16x32_bf16 v[6:9], v[228:231], v[220:223], v[6:9]
	v_mfma_f32_16x16x32_bf16 v[2:5], v[236:239], v[220:223], v[2:5]
	v_mfma_f32_16x16x32_bf16 v[54:57], v[232:235], v[188:191], v[54:57]
	v_mfma_f32_16x16x32_bf16 v[50:53], v[240:243], v[188:191], v[50:53]
	v_mfma_f32_16x16x32_bf16 v[38:41], v[232:235], v[196:199], v[38:41]
	v_mfma_f32_16x16x32_bf16 v[34:37], v[240:243], v[196:199], v[34:37]
	v_mfma_f32_16x16x32_bf16 v[22:25], v[232:235], v[216:219], v[22:25]
	v_mfma_f32_16x16x32_bf16 v[18:21], v[240:243], v[216:219], v[18:21]
	v_mfma_f32_16x16x32_bf16 v[6:9], v[232:235], v[224:227], v[6:9]
	v_mfma_f32_16x16x32_bf16 v[2:5], v[240:243], v[224:227], v[2:5]
	s_setprio 0
	s_add_i32 s44, s44, 2
	s_add_u32 s46, s46, 0x100
	s_addc_u32 s47, s47, 0
	s_cmp_gt_u32 s44, 5
	s_mov_b64 s[80:81], s[10:11]
	s_barrier
	s_cbranch_scc0 .LBB0_482
	v_lshl_add_u32 v142, s63, 8, v144
	v_ashrrev_i32_e32 v143, 31, v142
	v_lshl_add_u64 v[140:141], v[142:143], 2, s[38:39]
	global_load_dword v216, v[140:141], off
	global_load_dword v218, v[140:141], off offset:64
	global_load_dword v220, v[140:141], off offset:128
	global_load_dword v222, v[140:141], off offset:192
	global_load_dword v224, v[140:141], off offset:512
	global_load_dword v226, v[140:141], off offset:576
	global_load_dword v228, v[140:141], off offset:640
	global_load_dword v230, v[140:141], off offset:704
	v_lshl_or_b32 v148, s62, 8, v146
	v_ashrrev_i32_e32 v149, 31, v148
	s_mov_b32 s2, 0x80000
	s_mov_b64 s[4:5], 0x80000
	s_mov_b32 s62, s74
	s_mov_b32 s63, s41
	s_mov_b64 s[82:83], s[78:79]
	s_mov_b64 s[80:81], s[76:77]
	v_readlane_b32 s93, v251, 60
	s_waitcnt vmcnt(7)
	v_mov_b32_e32 v150, v216
	v_pk_mul_f32 v[128:129], v[128:129], v[150:151] op_sel_hi:[1,0]
	v_pk_mul_f32 v[126:127], v[126:127], v[150:151] op_sel_hi:[1,0]
	v_pk_mul_f32 v[122:123], v[122:123], v[150:151] op_sel_hi:[1,0]
	v_pk_mul_f32 v[124:125], v[124:125], v[150:151] op_sel_hi:[1,0]
	v_cvt_pk_bf16_f32 v126, v126, v127
	v_cvt_pk_bf16_f32 v127, v128, v129
	v_cvt_pk_bf16_f32 v128, v122, v123
	v_lshlrev_b64 v[122:123], 12, v[142:143]
	v_cvt_pk_bf16_f32 v129, v124, v125
	v_lshl_add_u64 v[122:123], s[56:57], 0, v[122:123]
	v_lshlrev_b64 v[124:125], 1, v[148:149]
	v_lshl_add_u64 v[122:123], v[122:123], 0, v[124:125]
	global_store_dwordx4 v[122:123], v[126:129], off
	v_pk_mul_f32 v[120:121], v[120:121], v[150:151] op_sel_hi:[1,0]
	v_pk_mul_f32 v[118:119], v[118:119], v[150:151] op_sel_hi:[1,0]
	v_pk_mul_f32 v[126:127], v[116:117], v[150:151] op_sel_hi:[1,0]
	v_pk_mul_f32 v[116:117], v[114:115], v[150:151] op_sel_hi:[1,0]
	v_cvt_pk_bf16_f32 v114, v118, v119
	v_cvt_pk_bf16_f32 v115, v120, v121
	v_cvt_pk_bf16_f32 v116, v116, v117
	v_cvt_pk_bf16_f32 v117, v126, v127
	global_store_dwordx4 v[122:123], v[114:117], off offset:256
	s_nop 1
	v_or_b32_e32 v114, 16, v142
	v_ashrrev_i32_e32 v115, 31, v114
	v_lshl_add_u64 v[116:117], v[114:115], 2, s[38:39]
	s_waitcnt vmcnt(8)
	v_mov_b32_e32 v116, v218
	v_pk_mul_f32 v[110:111], v[110:111], v[116:117] op_sel_hi:[1,0]
	v_pk_mul_f32 v[118:119], v[108:109], v[116:117] op_sel_hi:[1,0]
	v_pk_mul_f32 v[108:109], v[106:107], v[116:117] op_sel_hi:[1,0]
	v_cvt_pk_bf16_f32 v106, v110, v111
	v_lshlrev_b64 v[110:111], 12, v[114:115]
	v_pk_mul_f32 v[112:113], v[112:113], v[116:117] op_sel_hi:[1,0]
	v_lshl_add_u64 v[110:111], s[56:57], 0, v[110:111]
	v_cvt_pk_bf16_f32 v107, v112, v113
	v_cvt_pk_bf16_f32 v108, v108, v109
	v_cvt_pk_bf16_f32 v109, v118, v119
	v_lshl_add_u64 v[110:111], v[110:111], 0, v[124:125]
	global_store_dwordx4 v[110:111], v[106:109], off
	v_pk_mul_f32 v[104:105], v[104:105], v[116:117] op_sel_hi:[1,0]
	v_pk_mul_f32 v[102:103], v[102:103], v[116:117] op_sel_hi:[1,0]
	v_pk_mul_f32 v[106:107], v[100:101], v[116:117] op_sel_hi:[1,0]
	v_pk_mul_f32 v[100:101], v[98:99], v[116:117] op_sel_hi:[1,0]
	v_cvt_pk_bf16_f32 v98, v102, v103
	v_cvt_pk_bf16_f32 v99, v104, v105
	v_cvt_pk_bf16_f32 v100, v100, v101
	v_cvt_pk_bf16_f32 v101, v106, v107
	global_store_dwordx4 v[110:111], v[98:101], off offset:256
	s_nop 1
	v_or_b32_e32 v98, 32, v142
	v_ashrrev_i32_e32 v99, 31, v98
	v_lshl_add_u64 v[100:101], v[98:99], 2, s[38:39]
	s_waitcnt vmcnt(9)
	v_mov_b32_e32 v100, v220
	v_pk_mul_f32 v[94:95], v[94:95], v[100:101] op_sel_hi:[1,0]
	v_pk_mul_f32 v[102:103], v[92:93], v[100:101] op_sel_hi:[1,0]
	v_pk_mul_f32 v[92:93], v[90:91], v[100:101] op_sel_hi:[1,0]
	v_cvt_pk_bf16_f32 v90, v94, v95
	v_lshlrev_b64 v[94:95], 12, v[98:99]
	v_pk_mul_f32 v[96:97], v[96:97], v[100:101] op_sel_hi:[1,0]
	v_lshl_add_u64 v[94:95], s[56:57], 0, v[94:95]
	v_cvt_pk_bf16_f32 v91, v96, v97
	v_cvt_pk_bf16_f32 v92, v92, v93
	v_cvt_pk_bf16_f32 v93, v102, v103
	v_lshl_add_u64 v[94:95], v[94:95], 0, v[124:125]
	global_store_dwordx4 v[94:95], v[90:93], off
	v_pk_mul_f32 v[88:89], v[88:89], v[100:101] op_sel_hi:[1,0]
	v_pk_mul_f32 v[86:87], v[86:87], v[100:101] op_sel_hi:[1,0]
	v_pk_mul_f32 v[90:91], v[84:85], v[100:101] op_sel_hi:[1,0]
	v_pk_mul_f32 v[84:85], v[82:83], v[100:101] op_sel_hi:[1,0]
	v_cvt_pk_bf16_f32 v82, v86, v87
	v_cvt_pk_bf16_f32 v83, v88, v89
	v_cvt_pk_bf16_f32 v84, v84, v85
	v_cvt_pk_bf16_f32 v85, v90, v91
	global_store_dwordx4 v[94:95], v[82:85], off offset:256
	s_nop 1
	v_or_b32_e32 v82, 48, v142
	v_ashrrev_i32_e32 v83, 31, v82
	v_lshl_add_u64 v[84:85], v[82:83], 2, s[38:39]
	s_waitcnt vmcnt(10)
	v_mov_b32_e32 v84, v222
	v_pk_mul_f32 v[78:79], v[78:79], v[84:85] op_sel_hi:[1,0]
	v_pk_mul_f32 v[86:87], v[76:77], v[84:85] op_sel_hi:[1,0]
	v_pk_mul_f32 v[76:77], v[74:75], v[84:85] op_sel_hi:[1,0]
	v_cvt_pk_bf16_f32 v74, v78, v79
	v_lshlrev_b64 v[78:79], 12, v[82:83]
	v_pk_mul_f32 v[80:81], v[80:81], v[84:85] op_sel_hi:[1,0]
	v_lshl_add_u64 v[78:79], s[56:57], 0, v[78:79]
	v_cvt_pk_bf16_f32 v75, v80, v81
	v_cvt_pk_bf16_f32 v76, v76, v77
	v_cvt_pk_bf16_f32 v77, v86, v87
	v_lshl_add_u64 v[78:79], v[78:79], 0, v[124:125]
	global_store_dwordx4 v[78:79], v[74:77], off
	v_pk_mul_f32 v[72:73], v[72:73], v[84:85] op_sel_hi:[1,0]
	v_pk_mul_f32 v[70:71], v[70:71], v[84:85] op_sel_hi:[1,0]
	v_pk_mul_f32 v[74:75], v[68:69], v[84:85] op_sel_hi:[1,0]
	v_pk_mul_f32 v[68:69], v[66:67], v[84:85] op_sel_hi:[1,0]
	v_cvt_pk_bf16_f32 v66, v70, v71
	v_cvt_pk_bf16_f32 v67, v72, v73
	v_cvt_pk_bf16_f32 v68, v68, v69
	v_cvt_pk_bf16_f32 v69, v74, v75
	global_store_dwordx4 v[78:79], v[66:69], off offset:256
	s_waitcnt vmcnt(11)
	v_mov_b32_e32 v66, v224
	v_pk_mul_f32 v[64:65], v[64:65], v[66:67] op_sel_hi:[1,0]
	v_pk_mul_f32 v[62:63], v[62:63], v[66:67] op_sel_hi:[1,0]
	v_pk_mul_f32 v[68:69], v[60:61], v[66:67] op_sel_hi:[1,0]
	v_pk_mul_f32 v[60:61], v[58:59], v[66:67] op_sel_hi:[1,0]
	v_cvt_pk_bf16_f32 v59, v64, v65
	v_add_co_u32_e32 v64, vcc, s2, v122
	v_cvt_pk_bf16_f32 v58, v62, v63
	v_cvt_pk_bf16_f32 v60, v60, v61
	v_cvt_pk_bf16_f32 v61, v68, v69
	v_addc_co_u32_e32 v65, vcc, 0, v123, vcc
	global_store_dwordx4 v[64:65], v[58:61], off
	v_pk_mul_f32 v[56:57], v[56:57], v[66:67] op_sel_hi:[1,0]
	v_pk_mul_f32 v[54:55], v[54:55], v[66:67] op_sel_hi:[1,0]
	v_pk_mul_f32 v[58:59], v[52:53], v[66:67] op_sel_hi:[1,0]
	v_pk_mul_f32 v[52:53], v[50:51], v[66:67] op_sel_hi:[1,0]
	v_lshl_add_u64 v[62:63], v[122:123], 0, s[4:5]
	v_cvt_pk_bf16_f32 v50, v54, v55
	v_cvt_pk_bf16_f32 v51, v56, v57
	v_cvt_pk_bf16_f32 v52, v52, v53
	v_cvt_pk_bf16_f32 v53, v58, v59
	global_store_dwordx4 v[62:63], v[50:53], off offset:256
	s_mov_b32 s2, 0x90000
	s_mov_b64 s[4:5], 0x90000
	s_waitcnt vmcnt(12)
	v_mov_b32_e32 v50, v226
	v_pk_mul_f32 v[48:49], v[48:49], v[50:51] op_sel_hi:[1,0]
	v_pk_mul_f32 v[46:47], v[46:47], v[50:51] op_sel_hi:[1,0]
	v_pk_mul_f32 v[52:53], v[44:45], v[50:51] op_sel_hi:[1,0]
	v_pk_mul_f32 v[44:45], v[42:43], v[50:51] op_sel_hi:[1,0]
	v_cvt_pk_bf16_f32 v43, v48, v49
	v_add_co_u32_e32 v48, vcc, s2, v122
	v_cvt_pk_bf16_f32 v42, v46, v47
	v_cvt_pk_bf16_f32 v44, v44, v45
	v_cvt_pk_bf16_f32 v45, v52, v53
	v_addc_co_u32_e32 v49, vcc, 0, v123, vcc
	global_store_dwordx4 v[48:49], v[42:45], off
	v_pk_mul_f32 v[40:41], v[40:41], v[50:51] op_sel_hi:[1,0]
	v_pk_mul_f32 v[38:39], v[38:39], v[50:51] op_sel_hi:[1,0]
	v_pk_mul_f32 v[42:43], v[36:37], v[50:51] op_sel_hi:[1,0]
	v_pk_mul_f32 v[36:37], v[34:35], v[50:51] op_sel_hi:[1,0]
	v_lshl_add_u64 v[46:47], v[122:123], 0, s[4:5]
	v_cvt_pk_bf16_f32 v34, v38, v39
	v_cvt_pk_bf16_f32 v35, v40, v41
	v_cvt_pk_bf16_f32 v36, v36, v37
	v_cvt_pk_bf16_f32 v37, v42, v43
	global_store_dwordx4 v[46:47], v[34:37], off offset:256
	s_mov_b32 s2, 0xa0000
	s_mov_b64 s[4:5], 0xa0000
	s_waitcnt vmcnt(13)
	v_mov_b32_e32 v34, v228
	v_pk_mul_f32 v[32:33], v[32:33], v[34:35] op_sel_hi:[1,0]
	v_pk_mul_f32 v[30:31], v[30:31], v[34:35] op_sel_hi:[1,0]
	v_pk_mul_f32 v[36:37], v[28:29], v[34:35] op_sel_hi:[1,0]
	v_pk_mul_f32 v[28:29], v[26:27], v[34:35] op_sel_hi:[1,0]
	v_cvt_pk_bf16_f32 v27, v32, v33
	v_add_co_u32_e32 v32, vcc, s2, v122
	v_cvt_pk_bf16_f32 v26, v30, v31
	v_cvt_pk_bf16_f32 v28, v28, v29
	v_cvt_pk_bf16_f32 v29, v36, v37
	v_addc_co_u32_e32 v33, vcc, 0, v123, vcc
	global_store_dwordx4 v[32:33], v[26:29], off
	v_pk_mul_f32 v[24:25], v[24:25], v[34:35] op_sel_hi:[1,0]
	v_pk_mul_f32 v[22:23], v[22:23], v[34:35] op_sel_hi:[1,0]
	v_pk_mul_f32 v[26:27], v[20:21], v[34:35] op_sel_hi:[1,0]
	v_pk_mul_f32 v[20:21], v[18:19], v[34:35] op_sel_hi:[1,0]
	v_lshl_add_u64 v[30:31], v[122:123], 0, s[4:5]
	v_cvt_pk_bf16_f32 v18, v22, v23
	v_cvt_pk_bf16_f32 v19, v24, v25
	v_cvt_pk_bf16_f32 v20, v20, v21
	v_cvt_pk_bf16_f32 v21, v26, v27
	global_store_dwordx4 v[30:31], v[18:21], off offset:256
	s_mov_b32 s2, 0xb0000
	s_mov_b64 s[4:5], 0xb0000
	s_waitcnt vmcnt(14)
	v_mov_b32_e32 v18, v230
	v_pk_mul_f32 v[16:17], v[16:17], v[18:19] op_sel_hi:[1,0]
	v_pk_mul_f32 v[14:15], v[14:15], v[18:19] op_sel_hi:[1,0]
	v_pk_mul_f32 v[20:21], v[12:13], v[18:19] op_sel_hi:[1,0]
	v_pk_mul_f32 v[12:13], v[10:11], v[18:19] op_sel_hi:[1,0]
	v_cvt_pk_bf16_f32 v11, v16, v17
	v_add_co_u32_e32 v16, vcc, s2, v122
	v_cvt_pk_bf16_f32 v10, v14, v15
	v_cvt_pk_bf16_f32 v12, v12, v13
	v_cvt_pk_bf16_f32 v13, v20, v21
	v_addc_co_u32_e32 v17, vcc, 0, v123, vcc
	global_store_dwordx4 v[16:17], v[10:13], off
	v_pk_mul_f32 v[8:9], v[8:9], v[18:19] op_sel_hi:[1,0]
	v_pk_mul_f32 v[6:7], v[6:7], v[18:19] op_sel_hi:[1,0]
	v_pk_mul_f32 v[10:11], v[4:5], v[18:19] op_sel_hi:[1,0]
	v_pk_mul_f32 v[4:5], v[2:3], v[18:19] op_sel_hi:[1,0]
	v_lshl_add_u64 v[14:15], v[122:123], 0, s[4:5]
	v_cvt_pk_bf16_f32 v2, v6, v7
	v_cvt_pk_bf16_f32 v3, v8, v9
	v_cvt_pk_bf16_f32 v4, v4, v5
	v_cvt_pk_bf16_f32 v5, v10, v11
	s_and_b64 vcc, exec, s[6:7]
	global_store_dwordx4 v[14:15], v[2:5], off offset:256
	s_cbranch_vccz .LBB0_473
	v_readlane_b32 s4, v254, 12
	s_waitcnt vmcnt(0)
	v_readlane_b32 s5, v254, 13
	v_readlane_b32 s84, v251, 38
	v_readlane_b32 s18, v253, 0
	s_andn2_b64 vcc, exec, s[4:5]
	v_readlane_b32 s85, v251, 39
	v_readlane_b32 s86, v251, 40
	v_readlane_b32 s87, v251, 41
	v_readlane_b32 s14, v250, 63
	v_readlane_b32 s19, v253, 1
	s_cbranch_vccnz .LBB0_486
	s_barrier
